# loop-edge edit: back-edge bookkeeping moved into the last load part, next-K-tile pointer selection moved behind the head segment's reads
# baseline (speedup 1.0000x reference)
; #define PG8_STAGE(bufoff, gbase, voff) do { _Pragma("unroll") for (int _i = 0; _i < 2; ++_i) \
;         __builtin_amdgcn_global_load_lds((const unsigned*)((const char*)(gbase) + (voff)[_i]), (LAS unsigned*)(lds + (bufoff) + ldsw + _i * 8192), 16, 0, 0); } while (0)
; #define PG8_LDA(dst, b, h) do { _Pragma("unroll") for (int m = 0; m < 4; ++m) _Pragma("unroll") for (int k = 0; k < 2; ++k) dst[m][k] = *(const LAS bf16x8*)(lds + PG8_SA(b, h) + aoff + m * 2048 + k * 1024); } while (0)
; #define PG8_LDB(dst, b, h) do { _Pragma("unroll") for (int n = 0; n < 2; ++n) _Pragma("unroll") for (int k = 0; k < 2; ++k) dst[n][k] = *(const LAS bf16x8*)(lds + PG8_SB(b, h) + boff + n * 2048 + k * 1024); } while (0)
; #define PG8_MMA(ai, bj, At, Bt) do { __builtin_amdgcn_s_setprio(1); _Pragma("unroll") for (int m = 0; m < 4; ++m) _Pragma("unroll") for (int n = 0; n < 2; ++n) _Pragma("unroll") for (int k = 0; k < 2; ++k) \
;         acc[ai][bj][m][n] = __builtin_amdgcn_mfma_f32_16x16x32_bf16(Bt[n][k], At[m][k], acc[ai][bj][m][n], 0, 0, 0); __builtin_amdgcn_s_setprio(0); } while (0)
; #define PG8_WAIT_V(n) asm volatile("s_waitcnt vmcnt(" #n ")" ::: "memory")
; #define PG8_WAIT_L(n) asm volatile("s_waitcnt lgkmcnt(" #n ")" ::: "memory")
; #define PG8_BAR __builtin_amdgcn_s_barrier()
; #define PG8_SCHED __builtin_amdgcn_sched_barrier(0)
; template <class Epi, class Sched>
; __device__ __forceinline__ void gemm_phase(LAS unsigned char* lds, const Gemm g, const Sched& S, const Epi& E) {
;     ...
;         for (int t = 0; t < nt; t += 2) {
;             const bool last = (t == nt - 2);
;             const char* a1 = cA + (size_t)(t + 1) * kstep;
;             const char* a2 = last ? nA : cA + (size_t)(t + 2) * kstep; const char* b2 = last ? nB : cB + (size_t)(t + 2) * kstep;
;             const char* a3 = a2 + kstep; const char* b3 = b2 + kstep;
;             PG8_LDB(B0, 0, 0); PG8_LDB(B1, 0, 1); PG8_SCHED; PG8_LDA(At, 0, 0); PG8_STAGE(PG8_SA(1, 1), a1 + hstepA, voffA);
;             PG8_WAIT_V(8); PG8_WAIT_L(0); PG8_BAR; PG8_MMA(0, 0, At, B0); PG8_MMA(0, 1, At, B1); PG8_BAR; PG8_SCHED;
;             PG8_LDA(At, 0, 1); PG8_STAGE(PG8_SB(0, 0), b2, voffB); PG8_STAGE(PG8_SB(0, 1), b2 + hstepB, voffB); PG8_STAGE(PG8_SA(0, 0), a2, voffA);
;             PG8_WAIT_V(8); PG8_WAIT_L(0); PG8_BAR; PG8_MMA(1, 0, At, B0); PG8_MMA(1, 1, At, B1); PG8_BAR; PG8_SCHED;
.Lp3_nobar:
.LBB0_31:
	s_add_i32 s52, 0, 0x10000
	s_add_i32 s54, 0, 0x14000
	v_add_u32_e32 v76, s52, v221
	v_add_u32_e32 v116, s54, v221
	ds_read_b128 v[40:43], v76
	ds_read_b128 v[44:47], v76 offset:1024
	ds_read_b128 v[72:75], v76 offset:2048
	ds_read_b128 v[76:79], v76 offset:3072
	ds_read_b128 v[88:91], v116
	ds_read_b128 v[108:111], v116 offset:1024
	ds_read_b128 v[112:115], v116 offset:2048
	ds_read_b128 v[116:119], v116 offset:3072
	s_add_i32 m0, s6, 0xc000
	ds_read_b128 v[128:131], v223
	ds_read_b128 v[148:151], v223 offset:1024
	ds_read_b128 v[152:155], v223 offset:2048
	ds_read_b128 v[156:159], v223 offset:3072
	ds_read_b128 v[160:163], v223 offset:4096
	ds_read_b128 v[172:175], v223 offset:5120
	ds_read_b128 v[176:179], v223 offset:6144
	ds_read_b128 v[188:191], v223 offset:7168
	global_load_lds_dwordx4 v204, s[0:1]
	s_add_i32 m0, s6, 0xe000
	s_nop 0
	global_load_lds_dwordx4 v206, s[0:1]
	s_add_u32 s16, s0, 0xfffc0080
	s_addc_u32 s17, s1, -1
	s_cmp_eq_u32 s25, 12
	s_cselect_b32 s41, s27, s17
	s_cselect_b32 s40, s26, s16
	s_cselect_b32 s17, s14, s23
	s_cselect_b32 s16, s15, s21
	s_waitcnt vmcnt(8)
	s_waitcnt lgkmcnt(0)
	s_barrier
	s_setprio 1
	s_waitcnt lgkmcnt(0)
	v_mfma_f32_16x16x32_bf16 v[60:63], v[40:43], v[128:131], v[60:63]
	v_mfma_f32_16x16x32_bf16 v[56:59], v[72:75], v[128:131], v[56:59]
	v_mfma_f32_16x16x32_bf16 v[96:99], v[40:43], v[152:155], v[96:99]
	v_mfma_f32_16x16x32_bf16 v[92:95], v[72:75], v[152:155], v[92:95]
	v_mfma_f32_16x16x32_bf16 v[136:139], v[40:43], v[160:163], v[136:139]
	v_mfma_f32_16x16x32_bf16 v[132:135], v[72:75], v[160:163], v[132:135]
	v_mfma_f32_16x16x32_bf16 v[124:127], v[40:43], v[176:179], v[124:127]
	v_mfma_f32_16x16x32_bf16 v[120:123], v[72:75], v[176:179], v[120:123]
	v_mfma_f32_16x16x32_bf16 v[60:63], v[44:47], v[148:151], v[60:63]
	v_mfma_f32_16x16x32_bf16 v[56:59], v[76:79], v[148:151], v[56:59]
	v_mfma_f32_16x16x32_bf16 v[96:99], v[44:47], v[156:159], v[96:99]
	v_mfma_f32_16x16x32_bf16 v[92:95], v[76:79], v[156:159], v[92:95]
	v_mfma_f32_16x16x32_bf16 v[136:139], v[44:47], v[172:175], v[136:139]
	v_mfma_f32_16x16x32_bf16 v[132:135], v[76:79], v[172:175], v[132:135]
	v_mfma_f32_16x16x32_bf16 v[124:127], v[44:47], v[188:191], v[124:127]
	v_mfma_f32_16x16x32_bf16 v[120:123], v[76:79], v[188:191], v[120:123]
	s_setprio 0
	s_setprio 1
	v_mfma_f32_16x16x32_bf16 v[184:187], v[88:91], v[128:131], v[184:187]
	v_mfma_f32_16x16x32_bf16 v[128:131], v[112:115], v[128:131], v[180:183]
	v_mfma_f32_16x16x32_bf16 v[144:147], v[88:91], v[160:163], v[144:147]
	v_mfma_f32_16x16x32_bf16 v[140:143], v[112:115], v[160:163], v[140:143]
	v_mfma_f32_16x16x32_bf16 v[104:107], v[88:91], v[176:179], v[104:107]
	v_mfma_f32_16x16x32_bf16 v[100:103], v[112:115], v[176:179], v[100:103]
	v_mfma_f32_16x16x32_bf16 v[184:187], v[108:111], v[148:151], v[184:187]
	v_mfma_f32_16x16x32_bf16 v[128:131], v[116:119], v[148:151], v[128:131]
	v_mfma_f32_16x16x32_bf16 v[148:151], v[88:91], v[152:155], v[168:171]
	v_mfma_f32_16x16x32_bf16 v[152:155], v[112:115], v[152:155], v[164:167]
	v_mfma_f32_16x16x32_bf16 v[144:147], v[108:111], v[172:175], v[144:147]
	v_mfma_f32_16x16x32_bf16 v[140:143], v[116:119], v[172:175], v[140:143]
	v_mfma_f32_16x16x32_bf16 v[104:107], v[108:111], v[188:191], v[104:107]
	v_mfma_f32_16x16x32_bf16 v[100:103], v[116:119], v[188:191], v[100:103]
	v_mfma_f32_16x16x32_bf16 v[148:151], v[108:111], v[156:159], v[148:151]
	v_mfma_f32_16x16x32_bf16 v[152:155], v[116:119], v[156:159], v[152:155]
	s_setprio 0
	s_barrier
	s_add_i32 s52, s52, s2
	s_mov_b32 m0, s52
	ds_read_b128 v[156:159], v223 offset:16384
	ds_read_b128 v[160:163], v223 offset:17408
	ds_read_b128 v[164:167], v223 offset:18432
	ds_read_b128 v[168:171], v223 offset:19456
	ds_read_b128 v[172:175], v223 offset:20480
	ds_read_b128 v[176:179], v223 offset:21504
	ds_read_b128 v[180:183], v223 offset:22528
	ds_read_b128 v[188:191], v223 offset:23552
	global_load_lds_dwordx4 v200, s[16:17]
	s_add_i32 m0, s52, 0x2000
	s_add_u32 s52, s16, 0x40000
	s_addc_u32 s53, s17, 0
	s_add_i32 s54, s54, s2
	global_load_lds_dwordx4 v196, s[16:17]
	s_mov_b32 m0, s54
	s_nop 0
	global_load_lds_dwordx4 v200, s[52:53]
	s_add_i32 m0, s54, 0x2000
	s_nop 0
	global_load_lds_dwordx4 v196, s[52:53]
	s_mov_b32 m0, s6
	s_nop 0
	global_load_lds_dwordx4 v202, s[40:41]
	s_mov_b32 m0, s44
	s_nop 0
	global_load_lds_dwordx4 v198, s[40:41]
	s_waitcnt vmcnt(8)
	s_waitcnt lgkmcnt(0)
	s_barrier
	s_setprio 1
	s_waitcnt lgkmcnt(0)
	v_mfma_f32_16x16x32_bf16 v[84:87], v[40:43], v[156:159], v[84:87]
	v_mfma_f32_16x16x32_bf16 v[80:83], v[72:75], v[156:159], v[80:83]
	v_mfma_f32_16x16x32_bf16 v[52:55], v[40:43], v[164:167], v[52:55]
	v_mfma_f32_16x16x32_bf16 v[48:51], v[72:75], v[164:167], v[48:51]
	v_mfma_f32_16x16x32_bf16 v[28:31], v[40:43], v[172:175], v[28:31]
	v_mfma_f32_16x16x32_bf16 v[24:27], v[72:75], v[172:175], v[24:27]
	v_mfma_f32_16x16x32_bf16 v[12:15], v[40:43], v[180:183], v[12:15]
	v_mfma_f32_16x16x32_bf16 v[8:11], v[72:75], v[180:183], v[8:11]
	v_mfma_f32_16x16x32_bf16 v[84:87], v[44:47], v[160:163], v[84:87]
	v_mfma_f32_16x16x32_bf16 v[80:83], v[76:79], v[160:163], v[80:83]
	v_mfma_f32_16x16x32_bf16 v[52:55], v[44:47], v[168:171], v[52:55]
	v_mfma_f32_16x16x32_bf16 v[48:51], v[76:79], v[168:171], v[48:51]
	v_mfma_f32_16x16x32_bf16 v[28:31], v[44:47], v[176:179], v[28:31]
	v_mfma_f32_16x16x32_bf16 v[24:27], v[76:79], v[176:179], v[24:27]
	v_mfma_f32_16x16x32_bf16 v[12:15], v[44:47], v[188:191], v[12:15]
	v_mfma_f32_16x16x32_bf16 v[8:11], v[76:79], v[188:191], v[8:11]
	s_setprio 0
	s_setprio 1
	v_mfma_f32_16x16x32_bf16 v[36:39], v[88:91], v[164:167], v[36:39]
	v_mfma_f32_16x16x32_bf16 v[32:35], v[112:115], v[164:167], v[32:35]
	v_mfma_f32_16x16x32_bf16 v[20:23], v[88:91], v[172:175], v[20:23]
	v_mfma_f32_16x16x32_bf16 v[16:19], v[112:115], v[172:175], v[16:19]
	v_mfma_f32_16x16x32_bf16 v[4:7], v[88:91], v[180:183], v[4:7]
	v_mfma_f32_16x16x32_bf16 v[0:3], v[112:115], v[180:183], v[0:3]
	v_mfma_f32_16x16x32_bf16 v[40:43], v[88:91], v[156:159], v[68:71]
	v_mfma_f32_16x16x32_bf16 v[44:47], v[112:115], v[156:159], v[64:67]
	v_mfma_f32_16x16x32_bf16 v[36:39], v[108:111], v[168:171], v[36:39]
	v_mfma_f32_16x16x32_bf16 v[32:35], v[116:119], v[168:171], v[32:35]
	v_mfma_f32_16x16x32_bf16 v[20:23], v[108:111], v[176:179], v[20:23]
	v_mfma_f32_16x16x32_bf16 v[16:19], v[116:119], v[176:179], v[16:19]
	v_mfma_f32_16x16x32_bf16 v[4:7], v[108:111], v[188:191], v[4:7]
	v_mfma_f32_16x16x32_bf16 v[0:3], v[116:119], v[188:191], v[0:3]
	v_mfma_f32_16x16x32_bf16 v[40:43], v[108:111], v[160:163], v[40:43]
	v_mfma_f32_16x16x32_bf16 v[44:47], v[116:119], v[160:163], v[44:47]
	s_setprio 0
	s_barrier
; #define PG8_STAGE(bufoff, gbase, voff) do { _Pragma("unroll") for (int _i = 0; _i < 2; ++_i) \
;         __builtin_amdgcn_global_load_lds((const unsigned*)((const char*)(gbase) + (voff)[_i]), (LAS unsigned*)(lds + (bufoff) + ldsw + _i * 8192), 16, 0, 0); } while (0)
; #define PG8_LDA(dst, b, h) do { _Pragma("unroll") for (int m = 0; m < 4; ++m) _Pragma("unroll") for (int k = 0; k < 2; ++k) dst[m][k] = *(const LAS bf16x8*)(lds + PG8_SA(b, h) + aoff + m * 2048 + k * 1024); } while (0)
; #define PG8_LDB(dst, b, h) do { _Pragma("unroll") for (int n = 0; n < 2; ++n) _Pragma("unroll") for (int k = 0; k < 2; ++k) dst[n][k] = *(const LAS bf16x8*)(lds + PG8_SB(b, h) + boff + n * 2048 + k * 1024); } while (0)
; #define PG8_MMA(ai, bj, At, Bt) do { __builtin_amdgcn_s_setprio(1); _Pragma("unroll") for (int m = 0; m < 4; ++m) _Pragma("unroll") for (int n = 0; n < 2; ++n) _Pragma("unroll") for (int k = 0; k < 2; ++k) \
;         acc[ai][bj][m][n] = __builtin_amdgcn_mfma_f32_16x16x32_bf16(Bt[n][k], At[m][k], acc[ai][bj][m][n], 0, 0, 0); __builtin_amdgcn_s_setprio(0); } while (0)
; #define PG8_WAIT_V(n) asm volatile("s_waitcnt vmcnt(" #n ")" ::: "memory")
; #define PG8_WAIT_L(n) asm volatile("s_waitcnt lgkmcnt(" #n ")" ::: "memory")
; #define PG8_BAR __builtin_amdgcn_s_barrier()
; #define PG8_SCHED __builtin_amdgcn_sched_barrier(0)
; template <class Epi, class Sched>
; __device__ __forceinline__ void gemm_phase(LAS unsigned char* lds, const Gemm g, const Sched& S, const Epi& E) {
;     ...
;             PG8_LDB(B0, 1, 0); PG8_LDB(B1, 1, 1); PG8_SCHED; PG8_LDA(At, 1, 0); PG8_STAGE(PG8_SA(0, 1), a2 + hstepA, voffA);
;             PG8_WAIT_V(8); PG8_WAIT_L(0); PG8_BAR; PG8_MMA(0, 0, At, B0); PG8_MMA(0, 1, At, B1); PG8_BAR; PG8_SCHED;
;             PG8_LDA(At, 1, 1); PG8_STAGE(PG8_SB(1, 0), b3, voffB); PG8_STAGE(PG8_SB(1, 1), b3 + hstepB, voffB); PG8_STAGE(PG8_SA(1, 0), a3, voffA);
;             PG8_WAIT_V(8); PG8_WAIT_L(0); PG8_BAR; PG8_MMA(1, 0, At, B0); PG8_MMA(1, 1, At, B1); PG8_BAR; PG8_SCHED;
;         }
;         if (wr == 0) PG8_BAR;
	s_add_i32 s52, 0, 0x18000
	s_add_i32 s53, 0, 0x1c000
	v_add_u32_e32 v76, s52, v221
	v_add_u32_e32 v116, s53, v221
	ds_read_b128 v[64:67], v76
	ds_read_b128 v[68:71], v76 offset:1024
	ds_read_b128 v[72:75], v76 offset:2048
	ds_read_b128 v[76:79], v76 offset:3072
	ds_read_b128 v[88:91], v116
	ds_read_b128 v[108:111], v116 offset:1024
	ds_read_b128 v[112:115], v116 offset:2048
	ds_read_b128 v[116:119], v116 offset:3072
	s_add_u32 s40, s40, 0x40000
	s_addc_u32 s41, s41, 0
	s_mov_b32 m0, s45
	ds_read_b128 v[156:159], v223 offset:32768
	ds_read_b128 v[160:163], v223 offset:33792
	ds_read_b128 v[164:167], v223 offset:34816
	ds_read_b128 v[172:175], v223 offset:35840
	ds_read_b128 v[176:179], v223 offset:36864
	ds_read_b128 v[188:191], v223 offset:37888
	ds_read_b128 v[192:195], v223 offset:38912
	ds_read_b128 v[208:211], v223 offset:39936
	global_load_lds_dwordx4 v202, s[40:41]
	s_mov_b32 m0, s46
	s_nop 0
	global_load_lds_dwordx4 v198, s[40:41]
	s_waitcnt vmcnt(8)
	s_waitcnt lgkmcnt(0)
	s_barrier
	s_setprio 1
	s_waitcnt lgkmcnt(0)
	v_mfma_f32_16x16x32_bf16 v[60:63], v[64:67], v[156:159], v[60:63]
	v_mfma_f32_16x16x32_bf16 v[56:59], v[72:75], v[156:159], v[56:59]
	v_mfma_f32_16x16x32_bf16 v[96:99], v[64:67], v[164:167], v[96:99]
	v_mfma_f32_16x16x32_bf16 v[92:95], v[72:75], v[164:167], v[92:95]
	v_mfma_f32_16x16x32_bf16 v[136:139], v[64:67], v[176:179], v[136:139]
	v_mfma_f32_16x16x32_bf16 v[132:135], v[72:75], v[176:179], v[132:135]
	v_mfma_f32_16x16x32_bf16 v[124:127], v[64:67], v[192:195], v[124:127]
	v_mfma_f32_16x16x32_bf16 v[120:123], v[72:75], v[192:195], v[120:123]
	v_mfma_f32_16x16x32_bf16 v[60:63], v[68:71], v[160:163], v[60:63]
	v_mfma_f32_16x16x32_bf16 v[56:59], v[76:79], v[160:163], v[56:59]
	v_mfma_f32_16x16x32_bf16 v[96:99], v[68:71], v[172:175], v[96:99]
	v_mfma_f32_16x16x32_bf16 v[92:95], v[76:79], v[172:175], v[92:95]
	v_mfma_f32_16x16x32_bf16 v[136:139], v[68:71], v[188:191], v[136:139]
	v_mfma_f32_16x16x32_bf16 v[132:135], v[76:79], v[188:191], v[132:135]
	v_mfma_f32_16x16x32_bf16 v[124:127], v[68:71], v[208:211], v[124:127]
	v_mfma_f32_16x16x32_bf16 v[120:123], v[76:79], v[208:211], v[120:123]
	s_setprio 0
	s_setprio 1
	v_mfma_f32_16x16x32_bf16 v[128:131], v[112:115], v[156:159], v[128:131]
	v_mfma_f32_16x16x32_bf16 v[168:171], v[88:91], v[156:159], v[184:187]
	v_mfma_f32_16x16x32_bf16 v[180:183], v[116:119], v[160:163], v[128:131]
	v_mfma_f32_16x16x32_bf16 v[128:131], v[88:91], v[164:167], v[148:151]
	v_mfma_f32_16x16x32_bf16 v[184:187], v[108:111], v[160:163], v[168:171]
	v_mfma_f32_16x16x32_bf16 v[168:171], v[108:111], v[172:175], v[128:131]
	v_mfma_f32_16x16x32_bf16 v[128:131], v[112:115], v[164:167], v[152:155]
	v_mfma_f32_16x16x32_bf16 v[164:167], v[116:119], v[172:175], v[128:131]
	v_mfma_f32_16x16x32_bf16 v[128:131], v[88:91], v[176:179], v[144:147]
	v_mfma_f32_16x16x32_bf16 v[144:147], v[108:111], v[188:191], v[128:131]
	v_mfma_f32_16x16x32_bf16 v[128:131], v[112:115], v[176:179], v[140:143]
	v_mfma_f32_16x16x32_bf16 v[104:107], v[88:91], v[192:195], v[104:107]
	v_mfma_f32_16x16x32_bf16 v[100:103], v[112:115], v[192:195], v[100:103]
	v_mfma_f32_16x16x32_bf16 v[140:143], v[116:119], v[188:191], v[128:131]
	v_mfma_f32_16x16x32_bf16 v[104:107], v[108:111], v[208:211], v[104:107]
	v_mfma_f32_16x16x32_bf16 v[100:103], v[116:119], v[208:211], v[100:103]
	s_setprio 0
	s_barrier
	s_add_u32 s98, s40, 0xfffc0080
	s_addc_u32 s99, s41, -1
	s_add_u32 s62, s16, 0x80
	s_addc_u32 s63, s17, 0
	s_add_i32 s40, s52, s2
	s_mov_b32 m0, s40
	ds_read_b128 v[128:131], v223 offset:49152
	ds_read_b128 v[148:151], v223 offset:50176
	ds_read_b128 v[152:155], v223 offset:51200
	ds_read_b128 v[156:159], v223 offset:52224
	ds_read_b128 v[160:163], v223 offset:53248
	ds_read_b128 v[172:175], v223 offset:54272
	ds_read_b128 v[176:179], v223 offset:55296
	ds_read_b128 v[188:191], v223 offset:56320
	global_load_lds_dwordx4 v200, s[62:63]
	s_add_i32 m0, s40, 0x2000
	s_add_u32 s16, s16, 0x40080
	s_addc_u32 s17, s17, 0
	s_add_i32 s40, s53, s2
	global_load_lds_dwordx4 v196, s[62:63]
	s_mov_b32 m0, s40
	s_nop 0
	global_load_lds_dwordx4 v200, s[16:17]
	s_add_i32 m0, s40, 0x2000
	s_nop 0
	global_load_lds_dwordx4 v196, s[16:17]
	s_mov_b32 m0, s47
	s_nop 0
	global_load_lds_dwordx4 v202, s[98:99]
	s_mov_b32 m0, s48
	s_nop 0
	global_load_lds_dwordx4 v198, s[98:99]
	s_add_i32 s25, s25, 2
	s_add_u32 s0, s0, 0x100
	s_addc_u32 s1, s1, 0
	s_add_u32 s21, s21, 0x100
	s_addc_u32 s23, s23, 0
	s_waitcnt vmcnt(8)
	s_waitcnt lgkmcnt(0)
	s_barrier
	s_setprio 1
	s_waitcnt lgkmcnt(0)
	v_mfma_f32_16x16x32_bf16 v[84:87], v[64:67], v[128:131], v[84:87]
	v_mfma_f32_16x16x32_bf16 v[80:83], v[72:75], v[128:131], v[80:83]
	v_mfma_f32_16x16x32_bf16 v[52:55], v[64:67], v[152:155], v[52:55]
	v_mfma_f32_16x16x32_bf16 v[48:51], v[72:75], v[152:155], v[48:51]
	v_mfma_f32_16x16x32_bf16 v[28:31], v[64:67], v[160:163], v[28:31]
	v_mfma_f32_16x16x32_bf16 v[24:27], v[72:75], v[160:163], v[24:27]
	v_mfma_f32_16x16x32_bf16 v[12:15], v[64:67], v[176:179], v[12:15]
	v_mfma_f32_16x16x32_bf16 v[8:11], v[72:75], v[176:179], v[8:11]
	v_mfma_f32_16x16x32_bf16 v[84:87], v[68:71], v[148:151], v[84:87]
	v_mfma_f32_16x16x32_bf16 v[80:83], v[76:79], v[148:151], v[80:83]
	v_mfma_f32_16x16x32_bf16 v[52:55], v[68:71], v[156:159], v[52:55]
	v_mfma_f32_16x16x32_bf16 v[48:51], v[76:79], v[156:159], v[48:51]
	v_mfma_f32_16x16x32_bf16 v[28:31], v[68:71], v[172:175], v[28:31]
	v_mfma_f32_16x16x32_bf16 v[24:27], v[76:79], v[172:175], v[24:27]
	v_mfma_f32_16x16x32_bf16 v[12:15], v[68:71], v[188:191], v[12:15]
	v_mfma_f32_16x16x32_bf16 v[8:11], v[76:79], v[188:191], v[8:11]
	s_setprio 0
	s_setprio 1
	v_mfma_f32_16x16x32_bf16 v[40:43], v[88:91], v[128:131], v[40:43]
	v_mfma_f32_16x16x32_bf16 v[68:71], v[108:111], v[148:151], v[40:43]
	v_mfma_f32_16x16x32_bf16 v[40:43], v[112:115], v[128:131], v[44:47]
	v_mfma_f32_16x16x32_bf16 v[36:39], v[88:91], v[152:155], v[36:39]
	v_mfma_f32_16x16x32_bf16 v[32:35], v[112:115], v[152:155], v[32:35]
	v_mfma_f32_16x16x32_bf16 v[20:23], v[88:91], v[160:163], v[20:23]
	v_mfma_f32_16x16x32_bf16 v[16:19], v[112:115], v[160:163], v[16:19]
	v_mfma_f32_16x16x32_bf16 v[4:7], v[88:91], v[176:179], v[4:7]
	v_mfma_f32_16x16x32_bf16 v[0:3], v[112:115], v[176:179], v[0:3]
	v_mfma_f32_16x16x32_bf16 v[64:67], v[116:119], v[148:151], v[40:43]
	v_mfma_f32_16x16x32_bf16 v[36:39], v[108:111], v[156:159], v[36:39]
	v_mfma_f32_16x16x32_bf16 v[32:35], v[116:119], v[156:159], v[32:35]
	v_mfma_f32_16x16x32_bf16 v[20:23], v[108:111], v[172:175], v[20:23]
	v_mfma_f32_16x16x32_bf16 v[16:19], v[116:119], v[172:175], v[16:19]
	v_mfma_f32_16x16x32_bf16 v[4:7], v[108:111], v[188:191], v[4:7]
	v_mfma_f32_16x16x32_bf16 v[0:3], v[116:119], v[188:191], v[0:3]
	s_setprio 0
	s_barrier
	s_cmp_gt_u32 s25, 13
	s_cbranch_scc0 .LBB0_31
	s_and_b64 vcc, exec, s[18:19]
	s_cbranch_vccz .LBB0_34
	s_barrier

; #define PG8_STAGE(bufoff, gbase, voff) do { _Pragma("unroll") for (int _i = 0; _i < 2; ++_i) \
;         __builtin_amdgcn_global_load_lds((const unsigned*)((const char*)(gbase) + (voff)[_i]), (LAS unsigned*)(lds + (bufoff) + ldsw + _i * 8192), 16, 0, 0); } while (0)
; #define PG8_LDA(dst, b, h) do { _Pragma("unroll") for (int m = 0; m < 4; ++m) _Pragma("unroll") for (int k = 0; k < 2; ++k) dst[m][k] = *(const LAS bf16x8*)(lds + PG8_SA(b, h) + aoff + m * 2048 + k * 1024); } while (0)
; #define PG8_LDB(dst, b, h) do { _Pragma("unroll") for (int n = 0; n < 2; ++n) _Pragma("unroll") for (int k = 0; k < 2; ++k) dst[n][k] = *(const LAS bf16x8*)(lds + PG8_SB(b, h) + boff + n * 2048 + k * 1024); } while (0)
; #define PG8_MMA(ai, bj, At, Bt) do { __builtin_amdgcn_s_setprio(1); _Pragma("unroll") for (int m = 0; m < 4; ++m) _Pragma("unroll") for (int n = 0; n < 2; ++n) _Pragma("unroll") for (int k = 0; k < 2; ++k) \
;         acc[ai][bj][m][n] = __builtin_amdgcn_mfma_f32_16x16x32_bf16(Bt[n][k], At[m][k], acc[ai][bj][m][n], 0, 0, 0); __builtin_amdgcn_s_setprio(0); } while (0)
; #define PG8_WAIT_V(n) asm volatile("s_waitcnt vmcnt(" #n ")" ::: "memory")
; #define PG8_WAIT_L(n) asm volatile("s_waitcnt lgkmcnt(" #n ")" ::: "memory")
; #define PG8_BAR __builtin_amdgcn_s_barrier()
; #define PG8_SCHED __builtin_amdgcn_sched_barrier(0)
; template <class Epi, class Sched>
; __device__ __forceinline__ void gemm_phase(LAS unsigned char* lds, const Gemm g, const Sched& S, const Epi& E) {
;     ...
;         for (int t = 0; t < nt; t += 2) {
;             const bool last = (t == nt - 2);
;             const char* a1 = cA + (size_t)(t + 1) * kstep;
;             const char* a2 = last ? nA : cA + (size_t)(t + 2) * kstep; const char* b2 = last ? nB : cB + (size_t)(t + 2) * kstep;
;             const char* a3 = a2 + kstep; const char* b3 = b2 + kstep;
;             PG8_LDB(B0, 0, 0); PG8_LDB(B1, 0, 1); PG8_SCHED; PG8_LDA(At, 0, 0); PG8_STAGE(PG8_SA(1, 1), a1 + hstepA, voffA);
;             PG8_WAIT_V(8); PG8_WAIT_L(0); PG8_BAR; PG8_MMA(0, 0, At, B0); PG8_MMA(0, 1, At, B1); PG8_BAR; PG8_SCHED;
;             PG8_LDA(At, 0, 1); PG8_STAGE(PG8_SB(0, 0), b2, voffB); PG8_STAGE(PG8_SB(0, 1), b2 + hstepB, voffB); PG8_STAGE(PG8_SA(0, 0), a2, voffA);
;             PG8_WAIT_V(8); PG8_WAIT_L(0); PG8_BAR; PG8_MMA(1, 0, At, B0); PG8_MMA(1, 1, At, B1); PG8_BAR; PG8_SCHED;
.Lp1_nobar:
.LBB0_280:
	s_add_i32 s44, 0, 0x10000
	v_add_u32_e32 v145, s44, v165
	s_add_i32 s46, 0, 0x14000
	ds_read_b128 v[148:151], v145
	ds_read_b128 v[152:155], v145 offset:1024
	ds_read_b128 v[156:159], v145 offset:2048
	ds_read_b128 v[160:163], v145 offset:3072
	v_add_u32_e32 v145, s46, v165
	ds_read_b128 v[168:171], v145
	ds_read_b128 v[172:175], v145 offset:1024
	ds_read_b128 v[176:179], v145 offset:2048
	ds_read_b128 v[180:183], v145 offset:3072
	s_add_i32 m0, s52, 0xc000
	ds_read_b128 v[184:187], v167
	ds_read_b128 v[188:191], v167 offset:1024
	ds_read_b128 v[192:195], v167 offset:2048
	ds_read_b128 v[196:199], v167 offset:3072
	ds_read_b128 v[200:203], v167 offset:4096
	ds_read_b128 v[204:207], v167 offset:5120
	ds_read_b128 v[208:211], v167 offset:6144
	ds_read_b128 v[214:217], v167 offset:7168
	global_load_lds_dwordx4 v140, s[24:25]
	s_add_i32 m0, s52, 0xe000
	s_nop 0
	global_load_lds_dwordx4 v142, s[24:25]
	s_add_u32 s26, s24, 0xfffc0080
	s_addc_u32 s27, s25, -1
	s_cmp_eq_u32 s43, 12
	s_cselect_b32 s37, s6, s27
	s_cselect_b32 s36, s14, s26
	s_cselect_b32 s27, s15, s42
	s_cselect_b32 s26, s17, s19
	s_waitcnt vmcnt(8)
	s_waitcnt lgkmcnt(0)
	s_barrier
	s_setprio 1
	s_waitcnt lgkmcnt(0)
	v_mfma_f32_16x16x32_bf16 v[124:127], v[148:151], v[184:187], v[124:127]
	v_mfma_f32_16x16x32_bf16 v[120:123], v[156:159], v[184:187], v[120:123]
	v_mfma_f32_16x16x32_bf16 v[108:111], v[148:151], v[192:195], v[108:111]
	v_mfma_f32_16x16x32_bf16 v[104:107], v[156:159], v[192:195], v[104:107]
	v_mfma_f32_16x16x32_bf16 v[92:95], v[148:151], v[200:203], v[92:95]
	v_mfma_f32_16x16x32_bf16 v[88:91], v[156:159], v[200:203], v[88:91]
	v_mfma_f32_16x16x32_bf16 v[76:79], v[148:151], v[208:211], v[76:79]
	v_mfma_f32_16x16x32_bf16 v[72:75], v[156:159], v[208:211], v[72:75]
	v_mfma_f32_16x16x32_bf16 v[124:127], v[152:155], v[188:191], v[124:127]
	v_mfma_f32_16x16x32_bf16 v[120:123], v[160:163], v[188:191], v[120:123]
	v_mfma_f32_16x16x32_bf16 v[108:111], v[152:155], v[196:199], v[108:111]
	v_mfma_f32_16x16x32_bf16 v[104:107], v[160:163], v[196:199], v[104:107]
	v_mfma_f32_16x16x32_bf16 v[92:95], v[152:155], v[204:207], v[92:95]
	v_mfma_f32_16x16x32_bf16 v[88:91], v[160:163], v[204:207], v[88:91]
	v_mfma_f32_16x16x32_bf16 v[76:79], v[152:155], v[214:217], v[76:79]
	v_mfma_f32_16x16x32_bf16 v[72:75], v[160:163], v[214:217], v[72:75]
	s_setprio 0
	s_setprio 1
	v_mfma_f32_16x16x32_bf16 v[116:119], v[168:171], v[184:187], v[116:119]
	v_mfma_f32_16x16x32_bf16 v[112:115], v[176:179], v[184:187], v[112:115]
	v_mfma_f32_16x16x32_bf16 v[100:103], v[168:171], v[192:195], v[100:103]
	v_mfma_f32_16x16x32_bf16 v[96:99], v[176:179], v[192:195], v[96:99]
	v_mfma_f32_16x16x32_bf16 v[84:87], v[168:171], v[200:203], v[84:87]
	v_mfma_f32_16x16x32_bf16 v[80:83], v[176:179], v[200:203], v[80:83]
	v_mfma_f32_16x16x32_bf16 v[68:71], v[168:171], v[208:211], v[68:71]
	v_mfma_f32_16x16x32_bf16 v[64:67], v[176:179], v[208:211], v[64:67]
	v_mfma_f32_16x16x32_bf16 v[116:119], v[172:175], v[188:191], v[116:119]
	v_mfma_f32_16x16x32_bf16 v[112:115], v[180:183], v[188:191], v[112:115]
	v_mfma_f32_16x16x32_bf16 v[100:103], v[172:175], v[196:199], v[100:103]
	v_mfma_f32_16x16x32_bf16 v[96:99], v[180:183], v[196:199], v[96:99]
	v_mfma_f32_16x16x32_bf16 v[84:87], v[172:175], v[204:207], v[84:87]
	v_mfma_f32_16x16x32_bf16 v[80:83], v[180:183], v[204:207], v[80:83]
	v_mfma_f32_16x16x32_bf16 v[68:71], v[172:175], v[214:217], v[68:71]
	v_mfma_f32_16x16x32_bf16 v[64:67], v[180:183], v[214:217], v[64:67]
	s_setprio 0
	s_barrier
	s_add_i32 s44, s44, s2
	s_mov_b32 m0, s44
	ds_read_b128 v[184:187], v167 offset:16384
	ds_read_b128 v[188:191], v167 offset:17408
	ds_read_b128 v[192:195], v167 offset:18432
	ds_read_b128 v[196:199], v167 offset:19456
	ds_read_b128 v[200:203], v167 offset:20480
	ds_read_b128 v[204:207], v167 offset:21504
	ds_read_b128 v[208:211], v167 offset:22528
	ds_read_b128 v[214:217], v167 offset:23552
	global_load_lds_dwordx4 v132, s[26:27]
	s_add_i32 m0, s44, 0x2000
	s_add_u32 s44, s26, 0x40000
	s_addc_u32 s45, s27, 0
	s_add_i32 s46, s46, s2
	global_load_lds_dwordx4 v128, s[26:27]
	s_mov_b32 m0, s46
	s_nop 0
	global_load_lds_dwordx4 v132, s[44:45]
	s_add_i32 m0, s46, 0x2000
	s_nop 0
	global_load_lds_dwordx4 v128, s[44:45]
	s_mov_b32 m0, s52
	s_nop 0
	global_load_lds_dwordx4 v134, s[36:37]
	s_mov_b32 m0, s53
	s_nop 0
	global_load_lds_dwordx4 v130, s[36:37]
	s_waitcnt vmcnt(8)
	s_waitcnt lgkmcnt(0)
	s_barrier
	s_setprio 1
	s_waitcnt lgkmcnt(0)
	v_mfma_f32_16x16x32_bf16 v[60:63], v[148:151], v[184:187], v[60:63]
	v_mfma_f32_16x16x32_bf16 v[56:59], v[156:159], v[184:187], v[56:59]
	v_mfma_f32_16x16x32_bf16 v[44:47], v[148:151], v[192:195], v[44:47]
	v_mfma_f32_16x16x32_bf16 v[40:43], v[156:159], v[192:195], v[40:43]
	v_mfma_f32_16x16x32_bf16 v[28:31], v[148:151], v[200:203], v[28:31]
	v_mfma_f32_16x16x32_bf16 v[24:27], v[156:159], v[200:203], v[24:27]
	v_mfma_f32_16x16x32_bf16 v[12:15], v[148:151], v[208:211], v[12:15]
	v_mfma_f32_16x16x32_bf16 v[8:11], v[156:159], v[208:211], v[8:11]
	v_mfma_f32_16x16x32_bf16 v[60:63], v[152:155], v[188:191], v[60:63]
	v_mfma_f32_16x16x32_bf16 v[56:59], v[160:163], v[188:191], v[56:59]
	v_mfma_f32_16x16x32_bf16 v[44:47], v[152:155], v[196:199], v[44:47]
	v_mfma_f32_16x16x32_bf16 v[40:43], v[160:163], v[196:199], v[40:43]
	v_mfma_f32_16x16x32_bf16 v[28:31], v[152:155], v[204:207], v[28:31]
	v_mfma_f32_16x16x32_bf16 v[24:27], v[160:163], v[204:207], v[24:27]
	v_mfma_f32_16x16x32_bf16 v[12:15], v[152:155], v[214:217], v[12:15]
	v_mfma_f32_16x16x32_bf16 v[8:11], v[160:163], v[214:217], v[8:11]
	s_setprio 0
	s_setprio 1
	v_mfma_f32_16x16x32_bf16 v[52:55], v[168:171], v[184:187], v[52:55]
	v_mfma_f32_16x16x32_bf16 v[48:51], v[176:179], v[184:187], v[48:51]
	v_mfma_f32_16x16x32_bf16 v[36:39], v[168:171], v[192:195], v[36:39]
	v_mfma_f32_16x16x32_bf16 v[32:35], v[176:179], v[192:195], v[32:35]
	v_mfma_f32_16x16x32_bf16 v[20:23], v[168:171], v[200:203], v[20:23]
	v_mfma_f32_16x16x32_bf16 v[16:19], v[176:179], v[200:203], v[16:19]
	v_mfma_f32_16x16x32_bf16 v[4:7], v[168:171], v[208:211], v[4:7]
	v_mfma_f32_16x16x32_bf16 v[0:3], v[176:179], v[208:211], v[0:3]
	v_mfma_f32_16x16x32_bf16 v[52:55], v[172:175], v[188:191], v[52:55]
	v_mfma_f32_16x16x32_bf16 v[48:51], v[180:183], v[188:191], v[48:51]
	v_mfma_f32_16x16x32_bf16 v[36:39], v[172:175], v[196:199], v[36:39]
	v_mfma_f32_16x16x32_bf16 v[32:35], v[180:183], v[196:199], v[32:35]
	v_mfma_f32_16x16x32_bf16 v[20:23], v[172:175], v[204:207], v[20:23]
	v_mfma_f32_16x16x32_bf16 v[16:19], v[180:183], v[204:207], v[16:19]
	v_mfma_f32_16x16x32_bf16 v[4:7], v[172:175], v[214:217], v[4:7]
	v_mfma_f32_16x16x32_bf16 v[0:3], v[180:183], v[214:217], v[0:3]
	s_setprio 0
	s_barrier
; #define PG8_STAGE(bufoff, gbase, voff) do { _Pragma("unroll") for (int _i = 0; _i < 2; ++_i) \
;         __builtin_amdgcn_global_load_lds((const unsigned*)((const char*)(gbase) + (voff)[_i]), (LAS unsigned*)(lds + (bufoff) + ldsw + _i * 8192), 16, 0, 0); } while (0)
; #define PG8_LDA(dst, b, h) do { _Pragma("unroll") for (int m = 0; m < 4; ++m) _Pragma("unroll") for (int k = 0; k < 2; ++k) dst[m][k] = *(const LAS bf16x8*)(lds + PG8_SA(b, h) + aoff + m * 2048 + k * 1024); } while (0)
; #define PG8_LDB(dst, b, h) do { _Pragma("unroll") for (int n = 0; n < 2; ++n) _Pragma("unroll") for (int k = 0; k < 2; ++k) dst[n][k] = *(const LAS bf16x8*)(lds + PG8_SB(b, h) + boff + n * 2048 + k * 1024); } while (0)
; #define PG8_MMA(ai, bj, At, Bt) do { __builtin_amdgcn_s_setprio(1); _Pragma("unroll") for (int m = 0; m < 4; ++m) _Pragma("unroll") for (int n = 0; n < 2; ++n) _Pragma("unroll") for (int k = 0; k < 2; ++k) \
;         acc[ai][bj][m][n] = __builtin_amdgcn_mfma_f32_16x16x32_bf16(Bt[n][k], At[m][k], acc[ai][bj][m][n], 0, 0, 0); __builtin_amdgcn_s_setprio(0); } while (0)
; #define PG8_WAIT_V(n) asm volatile("s_waitcnt vmcnt(" #n ")" ::: "memory")
; #define PG8_WAIT_L(n) asm volatile("s_waitcnt lgkmcnt(" #n ")" ::: "memory")
; #define PG8_BAR __builtin_amdgcn_s_barrier()
; #define PG8_SCHED __builtin_amdgcn_sched_barrier(0)
; template <class Epi, class Sched>
; __device__ __forceinline__ void gemm_phase(LAS unsigned char* lds, const Gemm g, const Sched& S, const Epi& E) {
;     ...
;             PG8_LDB(B0, 1, 0); PG8_LDB(B1, 1, 1); PG8_SCHED; PG8_LDA(At, 1, 0); PG8_STAGE(PG8_SA(0, 1), a2 + hstepA, voffA);
;             PG8_WAIT_V(8); PG8_WAIT_L(0); PG8_BAR; PG8_MMA(0, 0, At, B0); PG8_MMA(0, 1, At, B1); PG8_BAR; PG8_SCHED;
;             PG8_LDA(At, 1, 1); PG8_STAGE(PG8_SB(1, 0), b3, voffB); PG8_STAGE(PG8_SB(1, 1), b3 + hstepB, voffB); PG8_STAGE(PG8_SA(1, 0), a3, voffA);
;             PG8_WAIT_V(8); PG8_WAIT_L(0); PG8_BAR; PG8_MMA(1, 0, At, B0); PG8_MMA(1, 1, At, B1); PG8_BAR; PG8_SCHED;
;         }
;         if (wr == 0) PG8_BAR;
	s_add_i32 s44, 0, 0x18000
	v_add_u32_e32 v145, s44, v165
	s_add_i32 s45, 0, 0x1c000
	ds_read_b128 v[148:151], v145
	ds_read_b128 v[152:155], v145 offset:1024
	ds_read_b128 v[156:159], v145 offset:2048
	ds_read_b128 v[160:163], v145 offset:3072
	v_add_u32_e32 v145, s45, v165
	ds_read_b128 v[168:171], v145
	ds_read_b128 v[172:175], v145 offset:1024
	ds_read_b128 v[176:179], v145 offset:2048
	ds_read_b128 v[180:183], v145 offset:3072
	s_add_u32 s36, s36, 0x40000
	s_addc_u32 s37, s37, 0
	s_mov_b32 m0, s54
	ds_read_b128 v[184:187], v167 offset:32768
	ds_read_b128 v[188:191], v167 offset:33792
	ds_read_b128 v[192:195], v167 offset:34816
	ds_read_b128 v[196:199], v167 offset:35840
	ds_read_b128 v[200:203], v167 offset:36864
	ds_read_b128 v[204:207], v167 offset:37888
	ds_read_b128 v[208:211], v167 offset:38912
	ds_read_b128 v[214:217], v167 offset:39936
	global_load_lds_dwordx4 v134, s[36:37]
	s_mov_b32 m0, s55
	s_nop 0
	global_load_lds_dwordx4 v130, s[36:37]
	s_waitcnt vmcnt(8)
	s_waitcnt lgkmcnt(0)
	s_barrier
	s_setprio 1
	s_waitcnt lgkmcnt(0)
	v_mfma_f32_16x16x32_bf16 v[124:127], v[148:151], v[184:187], v[124:127]
	v_mfma_f32_16x16x32_bf16 v[120:123], v[156:159], v[184:187], v[120:123]
	v_mfma_f32_16x16x32_bf16 v[108:111], v[148:151], v[192:195], v[108:111]
	v_mfma_f32_16x16x32_bf16 v[104:107], v[156:159], v[192:195], v[104:107]
	v_mfma_f32_16x16x32_bf16 v[92:95], v[148:151], v[200:203], v[92:95]
	v_mfma_f32_16x16x32_bf16 v[88:91], v[156:159], v[200:203], v[88:91]
	v_mfma_f32_16x16x32_bf16 v[76:79], v[148:151], v[208:211], v[76:79]
	v_mfma_f32_16x16x32_bf16 v[72:75], v[156:159], v[208:211], v[72:75]
	v_mfma_f32_16x16x32_bf16 v[124:127], v[152:155], v[188:191], v[124:127]
	v_mfma_f32_16x16x32_bf16 v[120:123], v[160:163], v[188:191], v[120:123]
	v_mfma_f32_16x16x32_bf16 v[108:111], v[152:155], v[196:199], v[108:111]
	v_mfma_f32_16x16x32_bf16 v[104:107], v[160:163], v[196:199], v[104:107]
	v_mfma_f32_16x16x32_bf16 v[92:95], v[152:155], v[204:207], v[92:95]
	v_mfma_f32_16x16x32_bf16 v[88:91], v[160:163], v[204:207], v[88:91]
	v_mfma_f32_16x16x32_bf16 v[76:79], v[152:155], v[214:217], v[76:79]
	v_mfma_f32_16x16x32_bf16 v[72:75], v[160:163], v[214:217], v[72:75]
	s_setprio 0
	s_setprio 1
	v_mfma_f32_16x16x32_bf16 v[116:119], v[168:171], v[184:187], v[116:119]
	v_mfma_f32_16x16x32_bf16 v[112:115], v[176:179], v[184:187], v[112:115]
	v_mfma_f32_16x16x32_bf16 v[100:103], v[168:171], v[192:195], v[100:103]
	v_mfma_f32_16x16x32_bf16 v[96:99], v[176:179], v[192:195], v[96:99]
	v_mfma_f32_16x16x32_bf16 v[84:87], v[168:171], v[200:203], v[84:87]
	v_mfma_f32_16x16x32_bf16 v[80:83], v[176:179], v[200:203], v[80:83]
	v_mfma_f32_16x16x32_bf16 v[68:71], v[168:171], v[208:211], v[68:71]
	v_mfma_f32_16x16x32_bf16 v[64:67], v[176:179], v[208:211], v[64:67]
	v_mfma_f32_16x16x32_bf16 v[116:119], v[172:175], v[188:191], v[116:119]
	v_mfma_f32_16x16x32_bf16 v[112:115], v[180:183], v[188:191], v[112:115]
	v_mfma_f32_16x16x32_bf16 v[100:103], v[172:175], v[196:199], v[100:103]
	v_mfma_f32_16x16x32_bf16 v[96:99], v[180:183], v[196:199], v[96:99]
	v_mfma_f32_16x16x32_bf16 v[84:87], v[172:175], v[204:207], v[84:87]
	v_mfma_f32_16x16x32_bf16 v[80:83], v[180:183], v[204:207], v[80:83]
	v_mfma_f32_16x16x32_bf16 v[68:71], v[172:175], v[214:217], v[68:71]
	v_mfma_f32_16x16x32_bf16 v[64:67], v[180:183], v[214:217], v[64:67]
	s_setprio 0
	s_barrier
	s_add_u32 s98, s36, 0xfffc0080
	s_addc_u32 s99, s37, -1
	s_add_u32 s62, s26, 0x80
	s_addc_u32 s63, s27, 0
	s_add_i32 s36, s44, s2
	s_mov_b32 m0, s36
	ds_read_b128 v[184:187], v167 offset:49152
	ds_read_b128 v[188:191], v167 offset:50176
	ds_read_b128 v[192:195], v167 offset:51200
	ds_read_b128 v[196:199], v167 offset:52224
	ds_read_b128 v[200:203], v167 offset:53248
	ds_read_b128 v[204:207], v167 offset:54272
	ds_read_b128 v[208:211], v167 offset:55296
	ds_read_b128 v[214:217], v167 offset:56320
	global_load_lds_dwordx4 v132, s[62:63]
	s_add_i32 m0, s36, 0x2000
	s_add_u32 s26, s26, 0x40080
	s_addc_u32 s27, s27, 0
	s_add_i32 s36, s45, s2
	global_load_lds_dwordx4 v128, s[62:63]
	s_mov_b32 m0, s36
	s_nop 0
	global_load_lds_dwordx4 v132, s[26:27]
	s_add_i32 m0, s36, 0x2000
	s_nop 0
	global_load_lds_dwordx4 v128, s[26:27]
	s_mov_b32 m0, s56
	s_nop 0
	global_load_lds_dwordx4 v134, s[98:99]
	s_mov_b32 m0, s57
	s_nop 0
	global_load_lds_dwordx4 v130, s[98:99]
	s_add_i32 s43, s43, 2
	s_add_u32 s24, s24, 0x100
	s_addc_u32 s25, s25, 0
	s_add_u32 s19, s19, 0x100
	s_addc_u32 s42, s42, 0
	s_waitcnt vmcnt(8)
	s_waitcnt lgkmcnt(0)
	s_barrier
	s_setprio 1
	s_waitcnt lgkmcnt(0)
	v_mfma_f32_16x16x32_bf16 v[60:63], v[148:151], v[184:187], v[60:63]
	v_mfma_f32_16x16x32_bf16 v[56:59], v[156:159], v[184:187], v[56:59]
	v_mfma_f32_16x16x32_bf16 v[44:47], v[148:151], v[192:195], v[44:47]
	v_mfma_f32_16x16x32_bf16 v[40:43], v[156:159], v[192:195], v[40:43]
	v_mfma_f32_16x16x32_bf16 v[28:31], v[148:151], v[200:203], v[28:31]
	v_mfma_f32_16x16x32_bf16 v[24:27], v[156:159], v[200:203], v[24:27]
	v_mfma_f32_16x16x32_bf16 v[12:15], v[148:151], v[208:211], v[12:15]
	v_mfma_f32_16x16x32_bf16 v[8:11], v[156:159], v[208:211], v[8:11]
	v_mfma_f32_16x16x32_bf16 v[60:63], v[152:155], v[188:191], v[60:63]
	v_mfma_f32_16x16x32_bf16 v[56:59], v[160:163], v[188:191], v[56:59]
	v_mfma_f32_16x16x32_bf16 v[44:47], v[152:155], v[196:199], v[44:47]
	v_mfma_f32_16x16x32_bf16 v[40:43], v[160:163], v[196:199], v[40:43]
	v_mfma_f32_16x16x32_bf16 v[28:31], v[152:155], v[204:207], v[28:31]
	v_mfma_f32_16x16x32_bf16 v[24:27], v[160:163], v[204:207], v[24:27]
	v_mfma_f32_16x16x32_bf16 v[12:15], v[152:155], v[214:217], v[12:15]
	v_mfma_f32_16x16x32_bf16 v[8:11], v[160:163], v[214:217], v[8:11]
	s_setprio 0
	s_setprio 1
	v_mfma_f32_16x16x32_bf16 v[52:55], v[168:171], v[184:187], v[52:55]
	v_mfma_f32_16x16x32_bf16 v[48:51], v[176:179], v[184:187], v[48:51]
	v_mfma_f32_16x16x32_bf16 v[36:39], v[168:171], v[192:195], v[36:39]
	v_mfma_f32_16x16x32_bf16 v[32:35], v[176:179], v[192:195], v[32:35]
	v_mfma_f32_16x16x32_bf16 v[20:23], v[168:171], v[200:203], v[20:23]
	v_mfma_f32_16x16x32_bf16 v[16:19], v[176:179], v[200:203], v[16:19]
	v_mfma_f32_16x16x32_bf16 v[4:7], v[168:171], v[208:211], v[4:7]
	v_mfma_f32_16x16x32_bf16 v[0:3], v[176:179], v[208:211], v[0:3]
	v_mfma_f32_16x16x32_bf16 v[52:55], v[172:175], v[188:191], v[52:55]
	v_mfma_f32_16x16x32_bf16 v[48:51], v[180:183], v[188:191], v[48:51]
	v_mfma_f32_16x16x32_bf16 v[36:39], v[172:175], v[196:199], v[36:39]
	v_mfma_f32_16x16x32_bf16 v[32:35], v[180:183], v[196:199], v[32:35]
	v_mfma_f32_16x16x32_bf16 v[20:23], v[172:175], v[204:207], v[20:23]
	v_mfma_f32_16x16x32_bf16 v[16:19], v[180:183], v[204:207], v[16:19]
	v_mfma_f32_16x16x32_bf16 v[4:7], v[172:175], v[214:217], v[4:7]
	v_mfma_f32_16x16x32_bf16 v[0:3], v[180:183], v[214:217], v[0:3]
	s_setprio 0
	s_barrier
	s_cmp_gt_u32 s43, 13
	s_cbranch_scc0 .LBB0_280
	s_and_b64 vcc, exec, s[4:5]
	s_cbranch_vccz .LBB0_283
	s_barrier

; #define PG8_STAGE(bufoff, gbase, voff) do { _Pragma("unroll") for (int _i = 0; _i < 2; ++_i) \
;         __builtin_amdgcn_global_load_lds((const unsigned*)((const char*)(gbase) + (voff)[_i]), (LAS unsigned*)(lds + (bufoff) + ldsw + _i * 8192), 16, 0, 0); } while (0)
; #define PG8_LDA(dst, b, h) do { _Pragma("unroll") for (int m = 0; m < 4; ++m) _Pragma("unroll") for (int k = 0; k < 2; ++k) dst[m][k] = *(const LAS bf16x8*)(lds + PG8_SA(b, h) + aoff + m * 2048 + k * 1024); } while (0)
; #define PG8_LDB(dst, b, h) do { _Pragma("unroll") for (int n = 0; n < 2; ++n) _Pragma("unroll") for (int k = 0; k < 2; ++k) dst[n][k] = *(const LAS bf16x8*)(lds + PG8_SB(b, h) + boff + n * 2048 + k * 1024); } while (0)
; #define PG8_MMA(ai, bj, At, Bt) do { __builtin_amdgcn_s_setprio(1); _Pragma("unroll") for (int m = 0; m < 4; ++m) _Pragma("unroll") for (int n = 0; n < 2; ++n) _Pragma("unroll") for (int k = 0; k < 2; ++k) \
;         acc[ai][bj][m][n] = __builtin_amdgcn_mfma_f32_16x16x32_bf16(Bt[n][k], At[m][k], acc[ai][bj][m][n], 0, 0, 0); __builtin_amdgcn_s_setprio(0); } while (0)
; #define PG8_WAIT_V(n) asm volatile("s_waitcnt vmcnt(" #n ")" ::: "memory")
; #define PG8_WAIT_L(n) asm volatile("s_waitcnt lgkmcnt(" #n ")" ::: "memory")
; #define PG8_BAR __builtin_amdgcn_s_barrier()
; #define PG8_SCHED __builtin_amdgcn_sched_barrier(0)
; template <class Epi, class Sched>
; __device__ __forceinline__ void gemm_phase(LAS unsigned char* lds, const Gemm g, const Sched& S, const Epi& E) {
;     ...
;         for (int t = 0; t < nt; t += 2) {
;             const bool last = (t == nt - 2);
;             const char* a1 = cA + (size_t)(t + 1) * kstep;
;             const char* a2 = last ? nA : cA + (size_t)(t + 2) * kstep; const char* b2 = last ? nB : cB + (size_t)(t + 2) * kstep;
;             const char* a3 = a2 + kstep; const char* b3 = b2 + kstep;
;             PG8_LDB(B0, 0, 0); PG8_LDB(B1, 0, 1); PG8_SCHED; PG8_LDA(At, 0, 0); PG8_STAGE(PG8_SA(1, 1), a1 + hstepA, voffA);
;             PG8_WAIT_V(8); PG8_WAIT_L(0); PG8_BAR; PG8_MMA(0, 0, At, B0); PG8_MMA(0, 1, At, B1); PG8_BAR; PG8_SCHED;
;             PG8_LDA(At, 0, 1); PG8_STAGE(PG8_SB(0, 0), b2, voffB); PG8_STAGE(PG8_SB(0, 1), b2 + hstepB, voffB); PG8_STAGE(PG8_SA(0, 0), a2, voffA);
;             PG8_WAIT_V(8); PG8_WAIT_L(0); PG8_BAR; PG8_MMA(1, 0, At, B0); PG8_MMA(1, 1, At, B1); PG8_BAR; PG8_SCHED;
.Lp4_nobar:
.LBB0_510:
	s_add_i32 s52, 0, 0x10000
	s_add_i32 s54, 0, 0x14000
	v_add_u32_e32 v140, s52, v178
	v_add_u32_e32 v168, s54, v178
	ds_read_b128 v[128:131], v140
	ds_read_b128 v[132:135], v140 offset:1024
	ds_read_b128 v[136:139], v140 offset:2048
	ds_read_b128 v[140:143], v140 offset:3072
	ds_read_b128 v[144:147], v168
	ds_read_b128 v[148:151], v168 offset:1024
	ds_read_b128 v[152:155], v168 offset:2048
	ds_read_b128 v[168:171], v168 offset:3072
	s_add_i32 m0, s6, 0xc000
	ds_read_b128 v[172:175], v179
	ds_read_b128 v[180:183], v179 offset:1024
	ds_read_b128 v[184:187], v179 offset:2048
	ds_read_b128 v[188:191], v179 offset:3072
	ds_read_b128 v[192:195], v179 offset:4096
	ds_read_b128 v[196:199], v179 offset:5120
	ds_read_b128 v[200:203], v179 offset:6144
	ds_read_b128 v[204:207], v179 offset:7168
	global_load_lds_dwordx4 v164, s[24:25]
	s_add_i32 m0, s6, 0xe000
	s_nop 0
	global_load_lds_dwordx4 v166, s[24:25]
	s_add_u32 s26, s24, 0xfffc0080
	s_addc_u32 s27, s25, -1
	s_cmp_eq_u32 s51, 12
	s_cselect_b32 s37, s14, s27
	s_cselect_b32 s36, s15, s26
	s_cselect_b32 s27, s17, s50
	s_cselect_b32 s26, s19, s49
	s_waitcnt vmcnt(8)
	s_waitcnt lgkmcnt(0)
	s_barrier
	s_setprio 1
	s_waitcnt lgkmcnt(0)
	v_mfma_f32_16x16x32_bf16 v[124:127], v[128:131], v[172:175], v[124:127]
	v_mfma_f32_16x16x32_bf16 v[120:123], v[136:139], v[172:175], v[120:123]
	v_mfma_f32_16x16x32_bf16 v[112:115], v[128:131], v[184:187], v[112:115]
	v_mfma_f32_16x16x32_bf16 v[104:107], v[136:139], v[184:187], v[104:107]
	v_mfma_f32_16x16x32_bf16 v[96:99], v[128:131], v[192:195], v[96:99]
	v_mfma_f32_16x16x32_bf16 v[88:91], v[136:139], v[192:195], v[88:91]
	v_mfma_f32_16x16x32_bf16 v[80:83], v[128:131], v[200:203], v[80:83]
	v_mfma_f32_16x16x32_bf16 v[72:75], v[136:139], v[200:203], v[72:75]
	v_mfma_f32_16x16x32_bf16 v[124:127], v[132:135], v[180:183], v[124:127]
	v_mfma_f32_16x16x32_bf16 v[120:123], v[140:143], v[180:183], v[120:123]
	v_mfma_f32_16x16x32_bf16 v[112:115], v[132:135], v[188:191], v[112:115]
	v_mfma_f32_16x16x32_bf16 v[104:107], v[140:143], v[188:191], v[104:107]
	v_mfma_f32_16x16x32_bf16 v[96:99], v[132:135], v[196:199], v[96:99]
	v_mfma_f32_16x16x32_bf16 v[88:91], v[140:143], v[196:199], v[88:91]
	v_mfma_f32_16x16x32_bf16 v[80:83], v[132:135], v[204:207], v[80:83]
	v_mfma_f32_16x16x32_bf16 v[72:75], v[140:143], v[204:207], v[72:75]
	s_setprio 0
	s_setprio 1
	v_mfma_f32_16x16x32_bf16 v[116:119], v[144:147], v[172:175], v[116:119]
	v_mfma_f32_16x16x32_bf16 v[108:111], v[152:155], v[172:175], v[108:111]
	v_mfma_f32_16x16x32_bf16 v[100:103], v[144:147], v[184:187], v[100:103]
	v_mfma_f32_16x16x32_bf16 v[92:95], v[152:155], v[184:187], v[92:95]
	v_mfma_f32_16x16x32_bf16 v[84:87], v[144:147], v[192:195], v[84:87]
	v_mfma_f32_16x16x32_bf16 v[76:79], v[152:155], v[192:195], v[76:79]
	v_mfma_f32_16x16x32_bf16 v[68:71], v[144:147], v[200:203], v[68:71]
	v_mfma_f32_16x16x32_bf16 v[64:67], v[152:155], v[200:203], v[64:67]
	v_mfma_f32_16x16x32_bf16 v[116:119], v[148:151], v[180:183], v[116:119]
	v_mfma_f32_16x16x32_bf16 v[108:111], v[168:171], v[180:183], v[108:111]
	v_mfma_f32_16x16x32_bf16 v[100:103], v[148:151], v[188:191], v[100:103]
	v_mfma_f32_16x16x32_bf16 v[92:95], v[168:171], v[188:191], v[92:95]
	v_mfma_f32_16x16x32_bf16 v[84:87], v[148:151], v[196:199], v[84:87]
	v_mfma_f32_16x16x32_bf16 v[76:79], v[168:171], v[196:199], v[76:79]
	v_mfma_f32_16x16x32_bf16 v[68:71], v[148:151], v[204:207], v[68:71]
	v_mfma_f32_16x16x32_bf16 v[64:67], v[168:171], v[204:207], v[64:67]
	s_setprio 0
	s_barrier
	s_add_i32 s52, s52, s2
	s_mov_b32 m0, s52
	ds_read_b128 v[172:175], v179 offset:16384
	ds_read_b128 v[180:183], v179 offset:17408
	ds_read_b128 v[184:187], v179 offset:18432
	ds_read_b128 v[188:191], v179 offset:19456
	ds_read_b128 v[192:195], v179 offset:20480
	ds_read_b128 v[196:199], v179 offset:21504
	ds_read_b128 v[200:203], v179 offset:22528
	ds_read_b128 v[204:207], v179 offset:23552
	global_load_lds_dwordx4 v160, s[26:27]
	s_add_i32 m0, s52, 0x2000
	s_add_u32 s52, s26, 0x40000
	s_addc_u32 s53, s27, 0
	s_add_i32 s54, s54, s2
	global_load_lds_dwordx4 v156, s[26:27]
	s_mov_b32 m0, s54
	s_nop 0
	global_load_lds_dwordx4 v160, s[52:53]
	s_add_i32 m0, s54, 0x2000
	s_nop 0
	global_load_lds_dwordx4 v156, s[52:53]
	s_mov_b32 m0, s6
	s_nop 0
	global_load_lds_dwordx4 v162, s[36:37]
	s_mov_b32 m0, s40
	s_nop 0
	global_load_lds_dwordx4 v158, s[36:37]
	s_waitcnt vmcnt(8)
	s_waitcnt lgkmcnt(0)
	s_barrier
	s_setprio 1
	s_waitcnt lgkmcnt(0)
	v_mfma_f32_16x16x32_bf16 v[60:63], v[128:131], v[172:175], v[60:63]
	v_mfma_f32_16x16x32_bf16 v[56:59], v[136:139], v[172:175], v[56:59]
	v_mfma_f32_16x16x32_bf16 v[48:51], v[128:131], v[184:187], v[48:51]
	v_mfma_f32_16x16x32_bf16 v[40:43], v[136:139], v[184:187], v[40:43]
	v_mfma_f32_16x16x32_bf16 v[32:35], v[128:131], v[192:195], v[32:35]
	v_mfma_f32_16x16x32_bf16 v[24:27], v[136:139], v[192:195], v[24:27]
	v_mfma_f32_16x16x32_bf16 v[16:19], v[128:131], v[200:203], v[16:19]
	v_mfma_f32_16x16x32_bf16 v[8:11], v[136:139], v[200:203], v[8:11]
	v_mfma_f32_16x16x32_bf16 v[60:63], v[132:135], v[180:183], v[60:63]
	v_mfma_f32_16x16x32_bf16 v[56:59], v[140:143], v[180:183], v[56:59]
	v_mfma_f32_16x16x32_bf16 v[48:51], v[132:135], v[188:191], v[48:51]
	v_mfma_f32_16x16x32_bf16 v[40:43], v[140:143], v[188:191], v[40:43]
	v_mfma_f32_16x16x32_bf16 v[32:35], v[132:135], v[196:199], v[32:35]
	v_mfma_f32_16x16x32_bf16 v[24:27], v[140:143], v[196:199], v[24:27]
	v_mfma_f32_16x16x32_bf16 v[16:19], v[132:135], v[204:207], v[16:19]
	v_mfma_f32_16x16x32_bf16 v[8:11], v[140:143], v[204:207], v[8:11]
	s_setprio 0
	s_setprio 1
	v_mfma_f32_16x16x32_bf16 v[52:55], v[144:147], v[172:175], v[52:55]
	v_mfma_f32_16x16x32_bf16 v[44:47], v[152:155], v[172:175], v[44:47]
	v_mfma_f32_16x16x32_bf16 v[36:39], v[144:147], v[184:187], v[36:39]
	v_mfma_f32_16x16x32_bf16 v[28:31], v[152:155], v[184:187], v[28:31]
	v_mfma_f32_16x16x32_bf16 v[20:23], v[144:147], v[192:195], v[20:23]
	v_mfma_f32_16x16x32_bf16 v[12:15], v[152:155], v[192:195], v[12:15]
	v_mfma_f32_16x16x32_bf16 v[4:7], v[144:147], v[200:203], v[4:7]
	v_mfma_f32_16x16x32_bf16 v[0:3], v[152:155], v[200:203], v[0:3]
	v_mfma_f32_16x16x32_bf16 v[52:55], v[148:151], v[180:183], v[52:55]
	v_mfma_f32_16x16x32_bf16 v[44:47], v[168:171], v[180:183], v[44:47]
	v_mfma_f32_16x16x32_bf16 v[36:39], v[148:151], v[188:191], v[36:39]
	v_mfma_f32_16x16x32_bf16 v[28:31], v[168:171], v[188:191], v[28:31]
	v_mfma_f32_16x16x32_bf16 v[20:23], v[148:151], v[196:199], v[20:23]
	v_mfma_f32_16x16x32_bf16 v[12:15], v[168:171], v[196:199], v[12:15]
	v_mfma_f32_16x16x32_bf16 v[4:7], v[148:151], v[204:207], v[4:7]
	v_mfma_f32_16x16x32_bf16 v[0:3], v[168:171], v[204:207], v[0:3]
	s_setprio 0
	s_barrier
; #define PG8_STAGE(bufoff, gbase, voff) do { _Pragma("unroll") for (int _i = 0; _i < 2; ++_i) \
;         __builtin_amdgcn_global_load_lds((const unsigned*)((const char*)(gbase) + (voff)[_i]), (LAS unsigned*)(lds + (bufoff) + ldsw + _i * 8192), 16, 0, 0); } while (0)
; #define PG8_LDA(dst, b, h) do { _Pragma("unroll") for (int m = 0; m < 4; ++m) _Pragma("unroll") for (int k = 0; k < 2; ++k) dst[m][k] = *(const LAS bf16x8*)(lds + PG8_SA(b, h) + aoff + m * 2048 + k * 1024); } while (0)
; #define PG8_LDB(dst, b, h) do { _Pragma("unroll") for (int n = 0; n < 2; ++n) _Pragma("unroll") for (int k = 0; k < 2; ++k) dst[n][k] = *(const LAS bf16x8*)(lds + PG8_SB(b, h) + boff + n * 2048 + k * 1024); } while (0)
; #define PG8_MMA(ai, bj, At, Bt) do { __builtin_amdgcn_s_setprio(1); _Pragma("unroll") for (int m = 0; m < 4; ++m) _Pragma("unroll") for (int n = 0; n < 2; ++n) _Pragma("unroll") for (int k = 0; k < 2; ++k) \
;         acc[ai][bj][m][n] = __builtin_amdgcn_mfma_f32_16x16x32_bf16(Bt[n][k], At[m][k], acc[ai][bj][m][n], 0, 0, 0); __builtin_amdgcn_s_setprio(0); } while (0)
; #define PG8_WAIT_V(n) asm volatile("s_waitcnt vmcnt(" #n ")" ::: "memory")
; #define PG8_WAIT_L(n) asm volatile("s_waitcnt lgkmcnt(" #n ")" ::: "memory")
; #define PG8_BAR __builtin_amdgcn_s_barrier()
; #define PG8_SCHED __builtin_amdgcn_sched_barrier(0)
; template <class Epi, class Sched>
; __device__ __forceinline__ void gemm_phase(LAS unsigned char* lds, const Gemm g, const Sched& S, const Epi& E) {
;     ...
;             PG8_LDB(B0, 1, 0); PG8_LDB(B1, 1, 1); PG8_SCHED; PG8_LDA(At, 1, 0); PG8_STAGE(PG8_SA(0, 1), a2 + hstepA, voffA);
;             PG8_WAIT_V(8); PG8_WAIT_L(0); PG8_BAR; PG8_MMA(0, 0, At, B0); PG8_MMA(0, 1, At, B1); PG8_BAR; PG8_SCHED;
;             PG8_LDA(At, 1, 1); PG8_STAGE(PG8_SB(1, 0), b3, voffB); PG8_STAGE(PG8_SB(1, 1), b3 + hstepB, voffB); PG8_STAGE(PG8_SA(1, 0), a3, voffA);
;             PG8_WAIT_V(8); PG8_WAIT_L(0); PG8_BAR; PG8_MMA(1, 0, At, B0); PG8_MMA(1, 1, At, B1); PG8_BAR; PG8_SCHED;
;         }
;         if (wr == 0) PG8_BAR;
	s_add_i32 s52, 0, 0x18000
	s_add_i32 s53, 0, 0x1c000
	v_add_u32_e32 v140, s52, v178
	v_add_u32_e32 v168, s53, v178
	ds_read_b128 v[128:131], v140
	ds_read_b128 v[132:135], v140 offset:1024
	ds_read_b128 v[136:139], v140 offset:2048
	ds_read_b128 v[140:143], v140 offset:3072
	ds_read_b128 v[144:147], v168
	ds_read_b128 v[148:151], v168 offset:1024
	ds_read_b128 v[152:155], v168 offset:2048
	ds_read_b128 v[168:171], v168 offset:3072
	s_add_u32 s36, s36, 0x40000
	s_addc_u32 s37, s37, 0
	s_mov_b32 m0, s41
	ds_read_b128 v[172:175], v179 offset:32768
	ds_read_b128 v[180:183], v179 offset:33792
	ds_read_b128 v[184:187], v179 offset:34816
	ds_read_b128 v[188:191], v179 offset:35840
	ds_read_b128 v[192:195], v179 offset:36864
	ds_read_b128 v[196:199], v179 offset:37888
	ds_read_b128 v[200:203], v179 offset:38912
	ds_read_b128 v[204:207], v179 offset:39936
	global_load_lds_dwordx4 v162, s[36:37]
	s_mov_b32 m0, s42
	s_nop 0
	global_load_lds_dwordx4 v158, s[36:37]
	s_waitcnt vmcnt(8)
	s_waitcnt lgkmcnt(0)
	s_barrier
	s_setprio 1
	s_waitcnt lgkmcnt(0)
	v_mfma_f32_16x16x32_bf16 v[124:127], v[128:131], v[172:175], v[124:127]
	v_mfma_f32_16x16x32_bf16 v[120:123], v[136:139], v[172:175], v[120:123]
	v_mfma_f32_16x16x32_bf16 v[112:115], v[128:131], v[184:187], v[112:115]
	v_mfma_f32_16x16x32_bf16 v[104:107], v[136:139], v[184:187], v[104:107]
	v_mfma_f32_16x16x32_bf16 v[96:99], v[128:131], v[192:195], v[96:99]
	v_mfma_f32_16x16x32_bf16 v[88:91], v[136:139], v[192:195], v[88:91]
	v_mfma_f32_16x16x32_bf16 v[80:83], v[128:131], v[200:203], v[80:83]
	v_mfma_f32_16x16x32_bf16 v[72:75], v[136:139], v[200:203], v[72:75]
	v_mfma_f32_16x16x32_bf16 v[124:127], v[132:135], v[180:183], v[124:127]
	v_mfma_f32_16x16x32_bf16 v[120:123], v[140:143], v[180:183], v[120:123]
	v_mfma_f32_16x16x32_bf16 v[112:115], v[132:135], v[188:191], v[112:115]
	v_mfma_f32_16x16x32_bf16 v[104:107], v[140:143], v[188:191], v[104:107]
	v_mfma_f32_16x16x32_bf16 v[96:99], v[132:135], v[196:199], v[96:99]
	v_mfma_f32_16x16x32_bf16 v[88:91], v[140:143], v[196:199], v[88:91]
	v_mfma_f32_16x16x32_bf16 v[80:83], v[132:135], v[204:207], v[80:83]
	v_mfma_f32_16x16x32_bf16 v[72:75], v[140:143], v[204:207], v[72:75]
	s_setprio 0
	s_setprio 1
	v_mfma_f32_16x16x32_bf16 v[116:119], v[144:147], v[172:175], v[116:119]
	v_mfma_f32_16x16x32_bf16 v[108:111], v[152:155], v[172:175], v[108:111]
	v_mfma_f32_16x16x32_bf16 v[100:103], v[144:147], v[184:187], v[100:103]
	v_mfma_f32_16x16x32_bf16 v[92:95], v[152:155], v[184:187], v[92:95]
	v_mfma_f32_16x16x32_bf16 v[84:87], v[144:147], v[192:195], v[84:87]
	v_mfma_f32_16x16x32_bf16 v[76:79], v[152:155], v[192:195], v[76:79]
	v_mfma_f32_16x16x32_bf16 v[68:71], v[144:147], v[200:203], v[68:71]
	v_mfma_f32_16x16x32_bf16 v[64:67], v[152:155], v[200:203], v[64:67]
	v_mfma_f32_16x16x32_bf16 v[116:119], v[148:151], v[180:183], v[116:119]
	v_mfma_f32_16x16x32_bf16 v[108:111], v[168:171], v[180:183], v[108:111]
	v_mfma_f32_16x16x32_bf16 v[100:103], v[148:151], v[188:191], v[100:103]
	v_mfma_f32_16x16x32_bf16 v[92:95], v[168:171], v[188:191], v[92:95]
	v_mfma_f32_16x16x32_bf16 v[84:87], v[148:151], v[196:199], v[84:87]
	v_mfma_f32_16x16x32_bf16 v[76:79], v[168:171], v[196:199], v[76:79]
	v_mfma_f32_16x16x32_bf16 v[68:71], v[148:151], v[204:207], v[68:71]
	v_mfma_f32_16x16x32_bf16 v[64:67], v[168:171], v[204:207], v[64:67]
	s_setprio 0
	s_barrier
	s_add_u32 s98, s36, 0xfffc0080
	s_addc_u32 s99, s37, -1
	s_add_u32 s62, s26, 0x80
	s_addc_u32 s63, s27, 0
	s_add_i32 s36, s52, s2
	s_mov_b32 m0, s36
	ds_read_b128 v[172:175], v179 offset:49152
	ds_read_b128 v[180:183], v179 offset:50176
	ds_read_b128 v[184:187], v179 offset:51200
	ds_read_b128 v[188:191], v179 offset:52224
	ds_read_b128 v[192:195], v179 offset:53248
	ds_read_b128 v[196:199], v179 offset:54272
	ds_read_b128 v[200:203], v179 offset:55296
	ds_read_b128 v[204:207], v179 offset:56320
	global_load_lds_dwordx4 v160, s[62:63]
	s_add_i32 m0, s36, 0x2000
	s_add_u32 s26, s26, 0x40080
	s_addc_u32 s27, s27, 0
	s_add_i32 s36, s53, s2
	global_load_lds_dwordx4 v156, s[62:63]
	s_mov_b32 m0, s36
	s_nop 0
	global_load_lds_dwordx4 v160, s[26:27]
	s_add_i32 m0, s36, 0x2000
	s_nop 0
	global_load_lds_dwordx4 v156, s[26:27]
	s_mov_b32 m0, s44
	s_nop 0
	global_load_lds_dwordx4 v162, s[98:99]
	s_mov_b32 m0, s45
	s_nop 0
	global_load_lds_dwordx4 v158, s[98:99]
	s_add_i32 s51, s51, 2
	s_add_u32 s24, s24, 0x100
	s_addc_u32 s25, s25, 0
	s_add_u32 s49, s49, 0x100
	s_addc_u32 s50, s50, 0
	s_waitcnt vmcnt(8)
	s_waitcnt lgkmcnt(0)
	s_barrier
	s_setprio 1
	s_waitcnt lgkmcnt(0)
	v_mfma_f32_16x16x32_bf16 v[60:63], v[128:131], v[172:175], v[60:63]
	v_mfma_f32_16x16x32_bf16 v[56:59], v[136:139], v[172:175], v[56:59]
	v_mfma_f32_16x16x32_bf16 v[48:51], v[128:131], v[184:187], v[48:51]
	v_mfma_f32_16x16x32_bf16 v[40:43], v[136:139], v[184:187], v[40:43]
	v_mfma_f32_16x16x32_bf16 v[32:35], v[128:131], v[192:195], v[32:35]
	v_mfma_f32_16x16x32_bf16 v[24:27], v[136:139], v[192:195], v[24:27]
	v_mfma_f32_16x16x32_bf16 v[16:19], v[128:131], v[200:203], v[16:19]
	v_mfma_f32_16x16x32_bf16 v[8:11], v[136:139], v[200:203], v[8:11]
	v_mfma_f32_16x16x32_bf16 v[60:63], v[132:135], v[180:183], v[60:63]
	v_mfma_f32_16x16x32_bf16 v[56:59], v[140:143], v[180:183], v[56:59]
	v_mfma_f32_16x16x32_bf16 v[48:51], v[132:135], v[188:191], v[48:51]
	v_mfma_f32_16x16x32_bf16 v[40:43], v[140:143], v[188:191], v[40:43]
	v_mfma_f32_16x16x32_bf16 v[32:35], v[132:135], v[196:199], v[32:35]
	v_mfma_f32_16x16x32_bf16 v[24:27], v[140:143], v[196:199], v[24:27]
	v_mfma_f32_16x16x32_bf16 v[16:19], v[132:135], v[204:207], v[16:19]
	v_mfma_f32_16x16x32_bf16 v[8:11], v[140:143], v[204:207], v[8:11]
	s_setprio 0
	s_setprio 1
	v_mfma_f32_16x16x32_bf16 v[52:55], v[144:147], v[172:175], v[52:55]
	v_mfma_f32_16x16x32_bf16 v[44:47], v[152:155], v[172:175], v[44:47]
	v_mfma_f32_16x16x32_bf16 v[36:39], v[144:147], v[184:187], v[36:39]
	v_mfma_f32_16x16x32_bf16 v[28:31], v[152:155], v[184:187], v[28:31]
	v_mfma_f32_16x16x32_bf16 v[20:23], v[144:147], v[192:195], v[20:23]
	v_mfma_f32_16x16x32_bf16 v[12:15], v[152:155], v[192:195], v[12:15]
	v_mfma_f32_16x16x32_bf16 v[4:7], v[144:147], v[200:203], v[4:7]
	v_mfma_f32_16x16x32_bf16 v[0:3], v[152:155], v[200:203], v[0:3]
	v_mfma_f32_16x16x32_bf16 v[52:55], v[148:151], v[180:183], v[52:55]
	v_mfma_f32_16x16x32_bf16 v[44:47], v[168:171], v[180:183], v[44:47]
	v_mfma_f32_16x16x32_bf16 v[36:39], v[148:151], v[188:191], v[36:39]
	v_mfma_f32_16x16x32_bf16 v[28:31], v[168:171], v[188:191], v[28:31]
	v_mfma_f32_16x16x32_bf16 v[20:23], v[148:151], v[196:199], v[20:23]
	v_mfma_f32_16x16x32_bf16 v[12:15], v[168:171], v[196:199], v[12:15]
	v_mfma_f32_16x16x32_bf16 v[4:7], v[148:151], v[204:207], v[4:7]
	v_mfma_f32_16x16x32_bf16 v[0:3], v[168:171], v[204:207], v[0:3]
	s_setprio 0
	s_barrier
	s_cmp_gt_u32 s51, 13
	s_cbranch_scc0 .LBB0_510
	s_and_b64 vcc, exec, s[4:5]
	s_cbranch_vccz .LBB0_513
	s_barrier
